# MLA key loop: per-tile s_barrier replaced by per-wave LDS progress flags (R/W) for t>=1, waves 4-7 skewed s_sleep 12 per item (MFMA/VALU ping-pong across the 2 waves per SIMD)
# speedup vs baseline: 1.0165x; 1.0165x over previous
; DI int otid() { int t = threadIdx.x; asm volatile("" : "+v"(t)); return t; }
; DI void phase_attn_mla(const Params& P, bf16_t* og, unsigned char* smem, int L, int G) {
;   bf16_t* big = (bf16_t*)(P.ws + OFF_BIG);
;   const int tid = otid(), lane = tid & 63, w = tid >> 6, r = lane & 31, h = lane >> 5;
;   bf16_t* sK = (bf16_t*)smem; bf16_t* sVt = sK + 64 * 104;
;   const float sc = 0.10206207261596575f * LOG2E;
;   for (int it = L; it < 4096; it += G) {
;     int qt, bh; mla_item8(it, L, G, qt, bh);
;     const int b = bh >> 4, head = bh & 15;
;     const int t0 = qt * 256 + w * 32, t = t0 + r;
;     const size_t tok = (size_t)b * SEQ + t;
;     bf16x8 qf[6];
; #pragma unroll
;     for (int ks = 0; ks < 4; ++ks) qf[ks] = *(const bf16x8*)(big + ML_QN + tok * 1024 + head * 64 + ks * 16 + 8 * h);
; #pragma unroll
;     for (int ks = 0; ks < 2; ++ks) qf[4 + ks] = *(const bf16x8*)(big + ML_QR + tok * 512 + head * 32 + ks * 16 + 8 * h);
;     f32x16 o0, o1, s[2]; o_zero(o0, o1);
;     float m = NEGF, l = 0.f;
;     const bf16_t* knb = big + ML_KN + (size_t)b * SEQ * 1024 + head * 64;
;     const bf16_t* krb = big + ML_KR + (size_t)b * SEQ * 32;
;     const bf16_t* vb = big + ML_VT + (size_t)((b * 16 + head) * 64) * SEQ;
;     const int jhi = (qt * 256 + 255) >> 6;
.LBB0_769:
	s_or_b64 exec, exec, s[0:1]
	s_waitcnt lgkmcnt(0)
	v_cndmask_b32_e64 v0, 0, 1, s[4:5]
	v_cmp_ne_u32_e64 s[0:1], 1, v0
	v_mov_b32_e32 v2, v192
	s_andn2_b64 vcc, exec, s[4:5]
	v_writelane_b32 v246, s0, 32
	s_barrier
	s_nop 0
	v_writelane_b32 v246, s1, 33
	s_cbranch_vccnz .LBB0_793
	s_cmpk_lg_i32 s74, 0x100
	s_cselect_b64 s[0:1], -1, 0
	s_lshl_b32 s2, s70, 1
	s_andn2_b32 s2, s2, 63
	s_bfe_u32 s3, s70, 0x20003
	s_and_b32 s29, s70, 7
	s_or_b32 s28, s2, s3
	s_xor_b32 s30, s29, 7
	s_add_u32 s2, s72, 0x1a368800
	s_addc_u32 s3, s73, 0
	v_lshrrev_b32_e32 v0, 2, v2
	v_and_b32_e32 v4, 8, v0
	s_add_u32 s4, s72, 0x22368800
	v_lshlrev_b32_e32 v0, 3, v2
	s_movk_i32 s10, 0x100
	s_addc_u32 s5, s73, 0
	v_and_b32_e32 v8, 24, v0
	v_and_b32_e32 v3, 63, v2
	s_add_u32 s31, s72, 0x26368800
	v_ashrrev_i32_e32 v6, 3, v2
	v_bfe_u32 v9, v2, 2, 6
	s_waitcnt vmcnt(5)
	v_and_b32_e32 v138, 56, v0
	v_cmp_gt_i32_e64 s[12:13], s10, v2
	s_movk_i32 s10, 0xd0
	v_lshlrev_b32_e32 v12, 1, v8
	v_lshrrev_b32_e32 v13, 1, v2
	v_lshlrev_b32_e32 v14, 1, v2
	v_ashrrev_i32_e32 v5, 6, v2
	v_mov_b32_e32 v1, 0
	s_addc_u32 s33, s73, 0
	v_ashrrev_i32_e32 v7, 31, v6
	s_movk_i32 s11, 0x68
	v_lshlrev_b32_e32 v0, 1, v138
	s_waitcnt vmcnt(1)
	v_mad_u32_u24 v153, v9, s10, v12
	s_movk_i32 s14, 0x90
	v_and_b32_e32 v12, 19, v2
	v_and_b32_e32 v13, 4, v13
	v_and_b32_e32 v14, 8, v14
	v_or_b32_e32 v3, 32, v3
	s_movk_i32 s15, 0x1200
	v_and_b32_e32 v139, 31, v2
	s_add_u32 s34, s72, 0x19f68800
	v_lshlrev_b64 v[136:137], 11, v[6:7]
	v_lshlrev_b64 v[10:11], 12, v[6:7]
	v_mul_lo_u32 v7, v6, s11
	v_mad_u64_u32 v[142:143], s[10:11], v6, s14, v[0:1]
	v_or3_b32 v12, v13, v12, v14
	v_mul_u32_u24_e32 v173, 0x90, v3
	v_bfe_u32 v174, v2, 2, 4
	v_mul_lo_u32 v3, v5, s15
	v_lshlrev_b32_e32 v147, 5, v5
	s_addc_u32 s35, s73, 0
	v_lshl_add_u64 v[10:11], s[72:73], 0, v[10:11]
	s_mov_b64 s[10:11], 0x20000
	v_mul_u32_u24_e32 v12, 0xd0, v12
	v_and_b32_e32 v175, 8, v174
	v_mad_u32_u24 v5, v139, s14, v3
	v_bfe_u32 v146, v2, 3, 3
	v_mbcnt_hi_u32_b32 v182, -1, v193
	v_lshl_add_u32 v149, v7, 1, v0
	v_lshl_add_u64 v[144:145], v[136:137], 0, s[10:11]
	v_lshl_add_u32 v143, v4, 1, v12
	v_lshl_add_u32 v176, v175, 1, v12
	s_add_u32 s10, s72, 0x11f68800
	v_or_b32_e32 v177, v5, v175
	v_or_b32_e32 v5, v3, v0
	v_mul_u32_u24_e32 v12, 0x90, v146
	v_lshl_add_u64 v[2:3], v[10:11], 0, v[0:1]
	s_mov_b64 s[14:15], 0x2e368800
	v_and_b32_e32 v0, 64, v182
	v_lshlrev_b32_e32 v140, 6, v9
	v_mov_b32_e32 v141, v1
	v_mul_u32_u24_e32 v151, 0xd0, v9
	v_mul_u32_u24_e32 v172, 0x90, v139
	s_addc_u32 s11, s73, 0
	v_or_b32_e32 v148, 8, v146
	v_or_b32_e32 v150, 16, v146
	v_or_b32_e32 v152, 24, v146
	v_lshl_add_u64 v[154:155], v[2:3], 0, s[14:15]
	v_or_b32_e32 v178, 0x80, v9
	v_add_u32_e32 v179, 0x80, v6
	s_mov_b32 s15, 0
	s_waitcnt vmcnt(0)
	v_lshlrev_b32_e32 v156, 1, v4
	v_mov_b32_e32 v157, v1
	v_lshlrev_b32_e32 v158, 1, v138
	v_mov_b32_e32 v159, v1
	v_lshlrev_b32_e32 v160, 1, v8
	v_mov_b32_e32 v161, v1
	v_lshlrev_b32_e32 v180, 1, v7
	s_mov_b32 s36, 0xff61b1e6
	s_mov_b32 s37, 0x3e16c740
	v_add_u32_e32 v181, v5, v12
	v_xor_b32_e32 v183, 32, v182
	v_add_u32_e32 v184, 64, v0
	v_mov_b32_e32 v185, 0xff61b1e6
	s_mov_b32 s99, 0
	s_mov_b32 s38, s70
	s_branch .LBB0_772

; DI void phase_attn_mla(const Params& P, bf16_t* og, unsigned char* smem, int L, int G) {
;     ...
;     int qt, bh; mla_item8(it, L, G, qt, bh);
;     const int b = bh >> 4, head = bh & 15;
;     const int t0 = qt * 256 + w * 32, t = t0 + r;
;     const size_t tok = (size_t)b * SEQ + t;
;     bf16x8 qf[6];
; #pragma unroll
;     for (int ks = 0; ks < 4; ++ks) qf[ks] = *(const bf16x8*)(big + ML_QN + tok * 1024 + head * 64 + ks * 16 + 8 * h);
; #pragma unroll
;     for (int ks = 0; ks < 2; ++ks) qf[4 + ks] = *(const bf16x8*)(big + ML_QR + tok * 512 + head * 32 + ks * 16 + 8 * h);
;     f32x16 o0, o1, s[2]; o_zero(o0, o1);
;     float m = NEGF, l = 0.f;
;     const bf16_t* knb = big + ML_KN + (size_t)b * SEQ * 1024 + head * 64;
;     const bf16_t* krb = big + ML_KR + (size_t)b * SEQ * 32;
;     const bf16_t* vb = big + ML_VT + (size_t)((b * 16 + head) * 64) * SEQ;
;     const int jhi = (qt * 256 + 255) >> 6;
;     KVR8 R; kv96x8_fetch(R, knb, krb, vb, 0, tid);
;     __syncthreads();
;     kv96x8_store(R, sK, sVt, tid);
.LBB0_776:
	s_ashr_i32 s24, s26, 4
	v_lshl_add_u32 v162, s39, 8, v147
	v_or_b32_e32 v164, v162, v139
	s_ashr_i32 s25, s24, 31
	s_lshl_b64 s[20:21], s[24:25], 11
	v_ashrrev_i32_e32 v165, 31, v164
	v_lshl_add_u64 v[2:3], s[20:21], 0, v[164:165]
	s_and_b32 s14, s26, 15
	v_lshlrev_b64 v[4:5], 11, v[2:3]
	v_lshlrev_b64 v[2:3], 10, v[2:3]
	s_lshl_b32 s18, s14, 6
	s_mov_b32 s19, s15
	s_lshl_b32 s14, s14, 7
	v_lshl_add_u64 v[2:3], s[4:5], 0, v[2:3]
	s_lshl_b64 s[22:23], s[24:25], 22
	v_lshl_add_u64 v[2:3], v[2:3], 0, s[18:19]
	s_add_u32 s19, s31, s22
	s_addc_u32 s23, s33, s23
	s_add_u32 s22, s19, s14
	v_lshl_add_u64 v[4:5], s[2:3], 0, v[4:5]
	s_addc_u32 s23, s23, 0
	s_lshl_b64 s[24:25], s[24:25], 17
	v_lshl_add_u64 v[4:5], v[4:5], 0, s[14:15]
	s_add_u32 s24, s34, s24
	v_lshl_add_u64 v[4:5], v[4:5], 0, v[156:157]
	v_lshl_add_u64 v[2:3], v[2:3], 0, v[156:157]
	s_addc_u32 s25, s35, s25
	s_lshl_b32 s26, s26, 6
	v_lshl_add_u64 v[6:7], s[22:23], 0, v[136:137]
	global_load_dwordx4 v[80:83], v[4:5], off offset:32
	global_load_dwordx4 v[84:87], v[4:5], off offset:64
	global_load_dwordx4 v[88:91], v[4:5], off offset:96
	global_load_dwordx4 v[92:95], v[2:3], off
	s_ashr_i32 s27, s26, 31
	v_lshl_add_u64 v[6:7], v[6:7], 0, v[158:159]
	global_load_dwordx4 v[96:99], v[2:3], off offset:32
	global_load_dwordx4 v[12:15], v[6:7], off
	v_lshl_add_u64 v[2:3], s[24:25], 0, v[140:141]
	s_lshl_b64 s[26:27], s[26:27], 12
	v_lshl_add_u64 v[10:11], v[2:3], 0, v[160:161]
	global_load_dwordx4 v[6:9], v[10:11], off
	v_lshl_add_u64 v[166:167], v[154:155], 0, s[26:27]
	global_load_dwordx4 v[100:103], v[4:5], off
	s_nop 0
	global_load_dwordx4 v[2:5], v[166:167], off
	v_and_b32_e32 v250, 15, v192
	v_lshrrev_b32_e32 v252, 6, v192
	v_lshlrev_b32_e32 v250, 2, v250
	v_lshlrev_b32_e32 v252, 2, v252
	v_add_u32_e32 v250, 0x20000, v250
	v_add_u32_e32 v252, 0x20000, v252
	v_mov_b32_e32 v254, 0
	s_barrier
	s_mov_b64 s[100:101], exec
	s_mov_b64 exec, 1
	ds_write_b32 v252, v254
	ds_write_b32 v252, v254 offset:32
	s_mov_b64 exec, s[100:101]
	s_waitcnt vmcnt(3)
	ds_write_b128 v149, v[12:15]
	s_and_saveexec_b64 s[26:27], s[12:13]
	s_cbranch_execz .LBB0_778
	s_waitcnt vmcnt(2)
	ds_write_b128 v153, v[6:9] offset:128

; DI void phase_attn_mla(const Params& P, bf16_t* og, unsigned char* smem, int L, int G) {
;     ...
;     for (int j = 0; j <= jhi; ++j) {
;       const int key0 = j * 64, cb = j & 1;
;       __syncthreads();
;       if (j < jhi) kv96x8_store(R, sK + (cb ^ 1) * KVB96, sVt + (cb ^ 1) * KVB96, tid);
;       if (j + 1 < jhi) kv96x8_fetch(R, knb, krb, vb, key0 + 128, tid);
;       __builtin_amdgcn_sched_barrier(0);
.LBB0_779:
	s_and_b32 s40, s26, 1
	s_add_i32 s98, s26, 1
	v_mov_b32_e32 v254, s98
	s_cmp_eq_u32 s26, 0
	s_cbranch_scc0 .Lmy_mla_spin
	s_waitcnt lgkmcnt(0)
	s_barrier
	v_readfirstlane_b32 s100, v192
	s_cmp_lt_u32 s100, 0x100
	s_cbranch_scc1 .Lmy_mla_go
	s_sleep 12
	s_branch .Lmy_mla_go
.Lmy_mla_spin:
	ds_read_b32 v251, v250
	s_waitcnt lgkmcnt(0)
	v_cmp_gt_u32_e32 vcc, s26, v251
	s_cbranch_vccz .Lmy_mla_go
	s_add_i32 s99, s99, 1
	s_cmp_lt_u32 s99, 0x40000
	s_cbranch_scc1 .Lmy_mla_spin
.Lmy_mla_go:
	s_cmp_ge_u32 s26, s19
	s_cbranch_scc1 .LBB0_783
	s_xor_b32 s24, s40, 1
	s_mulk_i32 s24, 0x2c00
	s_lshl_b32 s25, s24, 1
	v_add3_u32 v0, s25, v180, v158
	s_waitcnt vmcnt(1)
	ds_write_b128 v0, v[108:111]
	s_and_saveexec_b64 s[22:23], s[12:13]
	v_add3_u32 v0, s25, v151, v160
	ds_write_b128 v0, v[104:107] offset:128
	s_or_b64 exec, exec, s[22:23]
	v_lshl_add_u32 v0, s24, 1, v142
	s_waitcnt vmcnt(0)
	ds_write_b128 v0, v[112:115] offset:13312
	s_mov_b64 s[100:101], exec
	s_mov_b64 exec, 1
	ds_write_b32 v252, v254 offset:32
	s_mov_b64 exec, s[100:101]

; template <int DQK, bool MASKED, int MODE, class MF>
; DI void attn_step(const bf16_t* sK, const bf16_t* sVt, const bf16x8 (&qf)[DQK / 16], f32x16& o0, f32x16& o1, float& m, float& l,
;                   float sc, const MF& mf, int lane, f32x16 (&s)[2], float invl, bool lanevalid = true) {
;   const int r = lane & 31, h = lane >> 5;
;   const int pr = kperm(r);
;   constexpr int KST = DQK + 8;
;   bf16x8 kf[2][DQK / 16];
; #pragma unroll
;   for (int sub = 0; sub < 2; ++sub)
; #pragma unroll
;     for (int ks = 0; ks < DQK / 16; ++ks) kf[sub][ks] = *(const bf16x8*)(sK + (sub * 32 + pr) * KST + ks * 16 + 8 * h);
;   __builtin_amdgcn_sched_barrier(0);
; #pragma unroll
;   for (int q = 0; q < 16; ++q) { s[0][q] = 0.f; s[1][q] = 0.f; }
; #pragma unroll
;   for (int ks = 0; ks < DQK / 16; ++ks) {
;     s[0] = MFMA(kf[0][ks], qf[ks], s[0]);
;     s[1] = MFMA(kf[1][ks], qf[ks], s[1]);
;   }
;   bf16x8 vf[2][2][2];
;   if (MODE != 1) {
; #pragma unroll
;     for (int sub = 0; sub < 2; ++sub)
; #pragma unroll
;       for (int s2 = 0; s2 < 2; ++s2) {
;         vf[sub][s2][0] = *(const bf16x8*)(sVt + r * 72 + sub * 32 + s2 * 16 + 8 * h);
;         vf[sub][s2][1] = *(const bf16x8*)(sVt + (32 + r) * 72 + sub * 32 + s2 * 16 + 8 * h);
;       }
;     __builtin_amdgcn_sched_barrier(0);
;   }
;   float mxr = -3.0e38f;
; #pragma unroll
;   for (int sub = 0; sub < 2; ++sub)
; #pragma unroll
;     for (int q = 0; q < 16; ++q) {
;       if (MASKED) { const int kk = sub * 32 + 16 * (q >> 3) + 8 * h + (q & 7); s[sub][q] = mf(kk) ? s[sub][q] : -3.0e38f; }
;       if (MODE != 2) mxr = fmaxf(mxr, s[sub][q]);
;     }
;   float alpha = 1.f;
;   if (MODE != 2) {
;     float mx = fmaxf(m, mxr * sc);
;     mx = fmaxf(mx, shx(mx, 32));
;     if (!MASKED) mx = lanevalid ? mx : m;
;     alpha = fexp2(m - mx);
;     m = mx;
;   }
;   const float moff = (!MASKED && !lanevalid) ? 1.0e30f : m;
;   float ps = 0.f;
; #pragma unroll
;   for (int sub = 0; sub < 2; ++sub)
; DI void phase_attn_mla(const Params& P, bf16_t* og, unsigned char* smem, int L, int G) {
;     ...
;       if (key0 <= t0 + 31) {
;         auto mf = [&](int kk) { return key0 + kk <= t; };
;         if (key0 + 63 > t0) attn_step<96, true, 0>(sK + cb * KVB96, sVt + cb * KVB96, qf, o0, o1, m, l, sc, mf, lane, s, 0.f);
;         else attn_step<96, false, 0>(sK + cb * KVB96, sVt + cb * KVB96, qf, o0, o1, m, l, sc, mf, lane, s, 0.f);
.LBB0_785:
	v_cmp_le_i32_e32 vcc, s14, v163
	s_and_saveexec_b64 s[22:23], vcc
	s_cbranch_execz .Lmy_mla_skip
	s_add_i32 s24, s14, 63
	s_mulk_i32 s40, 0x2c00
	v_cmp_le_i32_e32 vcc, s24, v162
	s_lshl_b32 s39, s40, 1
	v_max_f32_e32 v0, v186, v186
	s_and_saveexec_b64 s[24:25], vcc
	s_xor_b64 s[24:25], exec, s[24:25]
	s_cbranch_execz .LBB0_788
	v_lshl_add_u32 v14, s40, 1, v143
	ds_read_b128 v[2:5], v14
	ds_read_b128 v[6:9], v14 offset:32
	ds_read_b128 v[10:13], v14 offset:64
	ds_read_b128 v[116:119], v14 offset:96
	ds_read_b128 v[120:123], v14 offset:128
	ds_read_b128 v[124:127], v14 offset:160
	ds_read_b128 v[48:51], v14 offset:6656
	ds_read_b128 v[128:131], v14 offset:6688
	ds_read_b128 v[132:135], v14 offset:6720
	ds_read_b128 v[188:191], v14 offset:6752
	ds_read_b128 v[194:197], v14 offset:6784
	ds_read_b128 v[198:201], v14 offset:6816
	s_waitcnt lgkmcnt(11)
	v_mfma_f32_32x32x16_bf16 v[64:79], v[2:5], v[100:103], 0
	v_add3_u32 v2, s39, v172, v156
	v_add3_u32 v3, s39, v173, v156
	s_waitcnt lgkmcnt(10)
	v_mfma_f32_32x32x16_bf16 v[64:79], v[6:9], v[80:83], v[64:79]
	s_waitcnt lgkmcnt(5)
	v_mfma_f32_32x32x16_bf16 v[48:63], v[48:51], v[100:103], 0
	v_mfma_f32_32x32x16_bf16 v[64:79], v[10:13], v[84:87], v[64:79]
	s_waitcnt lgkmcnt(4)
	v_mfma_f32_32x32x16_bf16 v[48:63], v[128:131], v[80:83], v[48:63]
	v_mfma_f32_32x32x16_bf16 v[64:79], v[116:119], v[88:91], v[64:79]
	s_waitcnt lgkmcnt(3)
	v_mfma_f32_32x32x16_bf16 v[48:63], v[132:135], v[84:87], v[48:63]
	v_mfma_f32_32x32x16_bf16 v[64:79], v[120:123], v[92:95], v[64:79]
	s_waitcnt lgkmcnt(2)
	v_mfma_f32_32x32x16_bf16 v[48:63], v[188:191], v[88:91], v[48:63]
	v_mfma_f32_32x32x16_bf16 v[64:79], v[124:127], v[96:99], v[64:79]
	ds_read_b128 v[132:135], v2 offset:13312
	ds_read_b128 v[124:127], v2 offset:13344
	ds_read_b128 v[128:131], v3 offset:13312
	ds_read_b128 v[120:123], v3 offset:13344
	ds_read_b128 v[116:119], v2 offset:13376
	ds_read_b128 v[6:9], v2 offset:13408
	ds_read_b128 v[10:13], v3 offset:13376
	ds_read_b128 v[2:5], v3 offset:13408
	s_waitcnt lgkmcnt(9)
	v_mfma_f32_32x32x16_bf16 v[48:63], v[194:197], v[92:95], v[48:63]
	s_waitcnt lgkmcnt(8)
	v_mfma_f32_32x32x16_bf16 v[48:63], v[198:201], v[96:99], v[48:63]
	v_max3_f32 v14, v64, s36, v65
	v_max3_f32 v14, v14, v66, v67
	v_max3_f32 v14, v14, v68, v69
	v_max3_f32 v14, v14, v70, v71
	v_max3_f32 v14, v14, v72, v73
	v_max3_f32 v14, v14, v74, v75
	v_max3_f32 v14, v14, v76, v77
	v_max3_f32 v14, v14, v78, v79
	s_nop 3
	v_max3_f32 v14, v14, v48, v49
	v_max3_f32 v14, v14, v50, v51
	v_max3_f32 v14, v14, v52, v53
	v_max3_f32 v14, v14, v54, v55
	v_max3_f32 v14, v14, v56, v57
	v_max3_f32 v14, v14, v58, v59
	v_max3_f32 v14, v14, v60, v61
	v_max3_f32 v14, v14, v62, v63
	v_mul_f32_e32 v14, 0x3e16c740, v14
	v_cmp_lt_i32_e32 vcc, v183, v184
	v_max_f32_e32 v0, v0, v14
	s_nop 0
	v_cndmask_b32_e32 v14, v182, v183, vcc
	v_lshlrev_b32_e32 v14, 2, v14
	ds_bpermute_b32 v15, v14, v0
	s_waitcnt lgkmcnt(0)
	s_mov_b64 s[100:101], exec
	s_mov_b64 exec, 1
	ds_write_b32 v252, v254
	s_mov_b64 exec, s[100:101]
	v_max_f32_e32 v15, v15, v15
	v_max_f32_e32 v15, v0, v15
	v_fma_f32 v0, v64, s37, -v15
	v_fma_f32 v64, v65, s37, -v15
	v_exp_f32_e32 v65, v0
	v_exp_f32_e32 v64, v64
	v_fma_f32 v0, v66, s37, -v15
	v_exp_f32_e32 v66, v0
	v_fma_f32 v67, v67, s37, -v15
	v_exp_f32_e32 v67, v67
	v_fma_f32 v68, v68, s37, -v15
	v_sub_f32_e32 v0, v186, v15
	v_add_f32_e32 v186, 0, v65
	v_exp_f32_e32 v68, v68
	v_fma_f32 v69, v69, s37, -v15
	v_add_f32_e32 v186, v64, v186
	v_exp_f32_e32 v69, v69
	v_fma_f32 v70, v70, s37, -v15
	v_add_f32_e32 v186, v66, v186
	v_exp_f32_e32 v70, v70
	v_fma_f32 v71, v71, s37, -v15
	v_add_f32_e32 v186, v67, v186
	v_exp_f32_e32 v71, v71
	v_fma_f32 v72, v72, s37, -v15
	v_add_f32_e32 v186, v68, v186
	v_exp_f32_e32 v72, v72
	v_fma_f32 v73, v73, s37, -v15
	v_add_f32_e32 v186, v69, v186
	v_exp_f32_e32 v73, v73
	v_fma_f32 v74, v74, s37, -v15
	v_add_f32_e32 v186, v70, v186
	v_exp_f32_e32 v74, v74
	v_fma_f32 v75, v75, s37, -v15
	v_add_f32_e32 v186, v71, v186
	v_exp_f32_e32 v75, v75
	v_fma_f32 v76, v76, s37, -v15
	v_add_f32_e32 v186, v72, v186
	v_exp_f32_e32 v76, v76
	v_fma_f32 v77, v77, s37, -v15
	v_add_f32_e32 v186, v73, v186
	v_exp_f32_e32 v77, v77
	v_fma_f32 v78, v78, s37, -v15
	v_add_f32_e32 v186, v74, v186
	v_exp_f32_e32 v78, v78
	v_fma_f32 v79, v79, s37, -v15
	v_add_f32_e32 v186, v75, v186
	v_exp_f32_e32 v79, v79
	v_fma_f32 v48, v48, s37, -v15
	v_add_f32_e32 v186, v76, v186
	v_exp_f32_e32 v187, v48
	v_fma_f32 v48, v49, s37, -v15
	v_add_f32_e32 v186, v77, v186
	v_exp_f32_e32 v188, v48
	v_fma_f32 v48, v50, s37, -v15
	v_add_f32_e32 v186, v78, v186
	v_exp_f32_e32 v189, v48
	v_fma_f32 v49, v51, s37, -v15
	v_add_f32_e32 v48, v79, v186
	v_exp_f32_e32 v186, v49
	v_fma_f32 v49, v52, s37, -v15
	v_add_f32_e32 v48, v187, v48
	v_exp_f32_e32 v52, v49
	v_fma_f32 v49, v53, s37, -v15
	v_add_f32_e32 v48, v188, v48
	v_exp_f32_e32 v53, v49
	v_fma_f32 v49, v54, s37, -v15
	v_add_f32_e32 v48, v189, v48
	v_exp_f32_e32 v54, v49
	v_add_f32_e32 v48, v186, v48
	v_add_f32_e32 v48, v52, v48
	v_exp_f32_e32 v0, v0
	v_add_f32_e32 v48, v53, v48
	v_add_f32_e32 v190, v54, v48
	v_fma_f32 v48, v55, s37, -v15
	v_exp_f32_e32 v55, v48
	v_fma_f32 v48, v56, s37, -v15
	v_exp_f32_e32 v56, v48
	v_pk_mul_f32 v[46:47], v[46:47], v[0:1] op_sel_hi:[1,0]
	v_pk_mul_f32 v[44:45], v[44:45], v[0:1] op_sel_hi:[1,0]
	v_pk_mul_f32 v[42:43], v[42:43], v[0:1] op_sel_hi:[1,0]
	v_pk_mul_f32 v[40:41], v[40:41], v[0:1] op_sel_hi:[1,0]
	v_pk_mul_f32 v[38:39], v[38:39], v[0:1] op_sel_hi:[1,0]
	v_pk_mul_f32 v[36:37], v[36:37], v[0:1] op_sel_hi:[1,0]
	v_pk_mul_f32 v[34:35], v[34:35], v[0:1] op_sel_hi:[1,0]
; #define MFMA(a, b, c) __builtin_amdgcn_mfma_f32_32x32x16_bf16((a), (b), (c), 0, 0, 0)
; DI unsigned pack2(float a, float b) { f32x2_t v = {a, b}; bf16x2_t r = __builtin_convertvector(v, bf16x2_t); return __builtin_bit_cast(unsigned, r); }
; DI float shx(float v, int m) { return __shfl_xor(v, m, 64); }
; template <int DQK, bool MASKED, int MODE, class MF>
; DI void attn_step(const bf16_t* sK, const bf16_t* sVt, const bf16x8 (&qf)[DQK / 16], f32x16& o0, f32x16& o1, float& m, float& l,
;                   float sc, const MF& mf, int lane, f32x16 (&s)[2], float invl, bool lanevalid = true) {
;     ...
;     }
;   if (MODE != 2) {
;     ps += shx(ps, 32);
;     l = l * alpha + ps;
;   }
;   if (MODE == 1) return;
;   if (MODE == 0) {
; #pragma unroll
;     for (int q = 0; q < 16; ++q) { o0[q] *= alpha; o1[q] *= alpha; }
;   }
; #pragma unroll
;   for (int sub = 0; sub < 2; ++sub)
; #pragma unroll
;     for (int s2 = 0; s2 < 2; ++s2) {
;       union { bf16x8 v; unsigned u[4]; } pb;
; #pragma unroll
;       for (int e = 0; e < 4; ++e) pb.u[e] = pack2(s[sub][8 * s2 + 2 * e], s[sub][8 * s2 + 2 * e + 1]);
;       o0 = MFMA(vf[sub][s2][0], pb.v, o0);
;       o1 = MFMA(vf[sub][s2][1], pb.v, o1);
;     }
; }
; DI void phase_attn_mla(const Params& P, bf16_t* og, unsigned char* smem, int L, int G) {
;     ...
;         if (key0 + 63 > t0) attn_step<96, true, 0>(sK + cb * KVB96, sVt + cb * KVB96, qf, o0, o1, m, l, sc, mf, lane, s, 0.f);
	v_pk_mul_f32 v[32:33], v[32:33], v[0:1] op_sel_hi:[1,0]
	v_cvt_pk_bf16_f32 v48, v65, v64
	v_cvt_pk_bf16_f32 v49, v66, v67
	v_cvt_pk_bf16_f32 v50, v68, v69
	v_cvt_pk_bf16_f32 v51, v70, v71
	v_pk_mul_f32 v[30:31], v[30:31], v[0:1] op_sel_hi:[1,0]
	v_pk_mul_f32 v[28:29], v[28:29], v[0:1] op_sel_hi:[1,0]
	v_mfma_f32_32x32x16_bf16 v[32:47], v[132:135], v[48:51], v[32:47]
	v_mul_f32_e64 v26, v26, v0
	v_mul_f32_e64 v27, v27, v0
	v_mul_f32_e64 v24, v24, v0
	v_mul_f32_e64 v25, v25, v0
	v_mul_f32_e64 v22, v22, v0
	v_mul_f32_e64 v23, v23, v0
	v_pk_mul_f32 v[20:21], v[20:21], v[0:1] op_sel_hi:[1,0]
	v_pk_mul_f32 v[18:19], v[18:19], v[0:1] op_sel_hi:[1,0]
	v_pk_mul_f32 v[16:17], v[16:17], v[0:1] op_sel_hi:[1,0]
	v_fma_f32 v57, v57, s37, -v15
	v_exp_f32_e32 v57, v57
	v_mfma_f32_32x32x16_bf16 v[16:31], v[128:131], v[48:51], v[16:31]
	v_add_f32_e32 v48, v55, v190
	v_add_f32_e32 v64, v56, v48
	v_cvt_pk_bf16_f32 v48, v72, v73
	v_cvt_pk_bf16_f32 v49, v74, v75
	v_cvt_pk_bf16_f32 v50, v76, v77
	v_cvt_pk_bf16_f32 v51, v78, v79
	v_fma_f32 v58, v58, s37, -v15
	v_exp_f32_e32 v58, v58
	v_mfma_f32_32x32x16_bf16 v[32:47], v[124:127], v[48:51], v[32:47]
	v_fma_f32 v59, v59, s37, -v15
	v_exp_f32_e32 v59, v59
	v_add_f32_e32 v64, v57, v64
	v_add_f32_e32 v64, v58, v64
	v_add_f32_e32 v64, v59, v64
	v_mfma_f32_32x32x16_bf16 v[16:31], v[120:123], v[48:51], v[16:31]
	v_fma_f32 v48, v60, s37, -v15
	v_exp_f32_e32 v60, v48
	v_cvt_pk_bf16_f32 v48, v187, v188
	v_cvt_pk_bf16_f32 v49, v189, v186
	v_cvt_pk_bf16_f32 v50, v52, v53
	v_cvt_pk_bf16_f32 v51, v54, v55
	v_fma_f32 v53, v61, s37, -v15
	v_exp_f32_e32 v53, v53
	v_mfma_f32_32x32x16_bf16 v[32:47], v[116:119], v[48:51], v[32:47]
	v_fma_f32 v54, v62, s37, -v15
	v_exp_f32_e32 v54, v54
	v_fma_f32 v55, v63, s37, -v15
	v_exp_f32_e32 v55, v55
	v_add_f32_e32 v52, v60, v64
	v_mov_b32_e32 v186, v15
	v_mfma_f32_32x32x16_bf16 v[16:31], v[10:13], v[48:51], v[16:31]
	v_add_f32_e32 v10, v53, v52
	v_add_f32_e32 v10, v54, v10
	v_add_f32_e32 v48, v55, v10
	v_cvt_pk_bf16_f32 v10, v56, v57
	v_cvt_pk_bf16_f32 v11, v58, v59
	v_cvt_pk_bf16_f32 v12, v60, v53
	v_cvt_pk_bf16_f32 v13, v54, v55
	s_nop 1
	v_mfma_f32_32x32x16_bf16 v[32:47], v[6:9], v[10:13], v[32:47]
	ds_bpermute_b32 v6, v14, v48
	s_waitcnt lgkmcnt(0)
	v_add_f32_e32 v6, v48, v6
	v_fmac_f32_e32 v6, v165, v0
	v_mfma_f32_32x32x16_bf16 v[16:31], v[2:5], v[10:13], v[16:31]
	v_mov_b32_e32 v165, v6
.LBB0_788:
	s_andn2_saveexec_b64 s[24:25], s[24:25]
	s_cbranch_execz .LBB0_790
	v_lshl_add_u32 v14, s40, 1, v176
	ds_read_b128 v[2:5], v14
	ds_read_b128 v[6:9], v14 offset:32
	ds_read_b128 v[10:13], v14 offset:64
	ds_read_b128 v[116:119], v14 offset:96
	ds_read_b128 v[120:123], v14 offset:128
	ds_read_b128 v[124:127], v14 offset:160
	ds_read_b128 v[48:51], v14 offset:6656
	ds_read_b128 v[128:131], v14 offset:6688
	ds_read_b128 v[132:135], v14 offset:6720
	ds_read_b128 v[188:191], v14 offset:6752
	ds_read_b128 v[194:197], v14 offset:6784
	ds_read_b128 v[198:201], v14 offset:6816
	s_waitcnt lgkmcnt(11)
	v_mfma_f32_32x32x16_bf16 v[64:79], v[2:5], v[100:103], 0
	v_lshlrev_b32_e32 v2, 1, v175
	v_add3_u32 v3, s39, v172, v2
	v_add3_u32 v2, s39, v173, v2
	s_waitcnt lgkmcnt(10)
	v_mfma_f32_32x32x16_bf16 v[64:79], v[6:9], v[80:83], v[64:79]
	s_waitcnt lgkmcnt(5)
	v_mfma_f32_32x32x16_bf16 v[48:63], v[48:51], v[100:103], 0
	v_mfma_f32_32x32x16_bf16 v[64:79], v[10:13], v[84:87], v[64:79]
	s_waitcnt lgkmcnt(4)
	v_mfma_f32_32x32x16_bf16 v[48:63], v[128:131], v[80:83], v[48:63]
	v_mfma_f32_32x32x16_bf16 v[64:79], v[116:119], v[88:91], v[64:79]
	s_waitcnt lgkmcnt(3)
	v_mfma_f32_32x32x16_bf16 v[48:63], v[132:135], v[84:87], v[48:63]
	v_mfma_f32_32x32x16_bf16 v[64:79], v[120:123], v[92:95], v[64:79]
	s_waitcnt lgkmcnt(2)
	v_mfma_f32_32x32x16_bf16 v[48:63], v[188:191], v[88:91], v[48:63]
	v_mfma_f32_32x32x16_bf16 v[64:79], v[124:127], v[96:99], v[64:79]
	ds_read_b128 v[132:135], v3 offset:13312
	ds_read_b128 v[124:127], v3 offset:13344
	ds_read_b128 v[128:131], v2 offset:13312
	ds_read_b128 v[120:123], v2 offset:13344
	ds_read_b128 v[116:119], v3 offset:13376
	ds_read_b128 v[6:9], v3 offset:13408
	ds_read_b128 v[10:13], v2 offset:13376
	ds_read_b128 v[2:5], v2 offset:13408
	s_waitcnt lgkmcnt(9)
	v_mfma_f32_32x32x16_bf16 v[48:63], v[194:197], v[92:95], v[48:63]
	s_waitcnt lgkmcnt(8)
; DI float shx(float v, int m) { return __shfl_xor(v, m, 64); }
; template <int DQK, bool MASKED, int MODE, class MF>
; DI void attn_step(const bf16_t* sK, const bf16_t* sVt, const bf16x8 (&qf)[DQK / 16], f32x16& o0, f32x16& o1, float& m, float& l,
;                   float sc, const MF& mf, int lane, f32x16 (&s)[2], float invl, bool lanevalid = true) {
;     ...
;       if (MASKED) { const int kk = sub * 32 + 16 * (q >> 3) + 8 * h + (q & 7); s[sub][q] = mf(kk) ? s[sub][q] : -3.0e38f; }
;       if (MODE != 2) mxr = fmaxf(mxr, s[sub][q]);
;     }
;   float alpha = 1.f;
;   if (MODE != 2) {
;     float mx = fmaxf(m, mxr * sc);
;     mx = fmaxf(mx, shx(mx, 32));
	v_mfma_f32_32x32x16_bf16 v[48:63], v[198:201], v[96:99], v[48:63]
	v_add_u32_e32 v14, s14, v175
	v_cmp_le_i32_e32 vcc, v14, v164
	s_nop 1
	v_cndmask_b32_e32 v15, v185, v64, vcc
	v_cmp_lt_i32_e32 vcc, v14, v164
	s_nop 1
	v_cndmask_b32_e32 v64, v185, v65, vcc
	v_add_u32_e32 v65, 2, v14
	v_cmp_le_i32_e32 vcc, v65, v164
	s_nop 1
	v_cndmask_b32_e32 v65, v185, v66, vcc
	v_add_u32_e32 v66, 3, v14
	v_cmp_le_i32_e32 vcc, v66, v164
	s_nop 1
	v_cndmask_b32_e32 v66, v185, v67, vcc
	v_add_u32_e32 v67, 4, v14
	v_cmp_le_i32_e32 vcc, v67, v164
	s_nop 1
	v_cndmask_b32_e32 v67, v185, v68, vcc
	v_add_u32_e32 v68, 5, v14
	v_cmp_le_i32_e32 vcc, v68, v164
	s_nop 1
	v_cndmask_b32_e32 v68, v185, v69, vcc
	v_add_u32_e32 v69, 6, v14
	v_cmp_le_i32_e32 vcc, v69, v164
	s_nop 1
	v_cndmask_b32_e32 v69, v185, v70, vcc
	v_add_u32_e32 v70, s14, v174
	v_or_b32_e32 v187, 7, v70
	v_cmp_le_i32_e32 vcc, v187, v164
	v_add_u32_e32 v187, 16, v14
	s_nop 0
	v_cndmask_b32_e32 v71, v185, v71, vcc
	v_cmp_le_i32_e32 vcc, v187, v164
	v_add_u32_e32 v187, 17, v14
	s_nop 0
	v_cndmask_b32_e32 v72, v185, v72, vcc
	v_cmp_le_i32_e32 vcc, v187, v164
	v_add_u32_e32 v187, 18, v14
	s_nop 0
	v_cndmask_b32_e32 v73, v185, v73, vcc
	v_cmp_le_i32_e32 vcc, v187, v164
	v_add_u32_e32 v187, 19, v14
	s_nop 0
	v_cndmask_b32_e32 v74, v185, v74, vcc
	v_cmp_le_i32_e32 vcc, v187, v164
	v_add_u32_e32 v187, 20, v14
	s_nop 0
	v_cndmask_b32_e32 v75, v185, v75, vcc
	v_cmp_le_i32_e32 vcc, v187, v164
	v_add_u32_e32 v187, 21, v14
	s_nop 0
	v_cndmask_b32_e32 v76, v185, v76, vcc
	v_cmp_le_i32_e32 vcc, v187, v164
	v_add_u32_e32 v187, 22, v14
	s_nop 0
	v_cndmask_b32_e32 v77, v185, v77, vcc
	v_cmp_le_i32_e32 vcc, v187, v164
	v_or_b32_e32 v187, 23, v70
	s_nop 0
	v_cndmask_b32_e32 v78, v185, v78, vcc
	v_cmp_le_i32_e32 vcc, v187, v164
	v_add_u32_e32 v187, 32, v14
	s_nop 0
	v_cndmask_b32_e32 v79, v185, v79, vcc
	v_cmp_le_i32_e32 vcc, v187, v164
	v_add_u32_e32 v187, 33, v14
	s_nop 0
	v_cndmask_b32_e32 v48, v185, v48, vcc
	v_cmp_le_i32_e32 vcc, v187, v164
	v_add_u32_e32 v187, 34, v14
	s_nop 0
	v_cndmask_b32_e32 v49, v185, v49, vcc
	v_cmp_le_i32_e32 vcc, v187, v164
	v_add_u32_e32 v187, 35, v14
	s_nop 0
	v_cndmask_b32_e32 v50, v185, v50, vcc
	v_cmp_le_i32_e32 vcc, v187, v164
	v_add_u32_e32 v187, 36, v14
	s_nop 0
	v_cndmask_b32_e32 v51, v185, v51, vcc
	v_cmp_le_i32_e32 vcc, v187, v164
	v_add_u32_e32 v187, 37, v14
	s_nop 0
	v_cndmask_b32_e32 v52, v185, v52, vcc
	v_cmp_le_i32_e32 vcc, v187, v164
	v_add_u32_e32 v187, 38, v14
	s_nop 0
	v_cndmask_b32_e32 v53, v185, v53, vcc
	v_cmp_le_i32_e32 vcc, v187, v164
	v_or_b32_e32 v187, 39, v70
	s_nop 0
	v_cndmask_b32_e32 v54, v185, v54, vcc
	v_cmp_le_i32_e32 vcc, v187, v164
	v_add_u32_e32 v187, 48, v14
	s_nop 0
	v_cndmask_b32_e32 v55, v185, v55, vcc
	v_cmp_le_i32_e32 vcc, v187, v164
	v_add_u32_e32 v187, 49, v14
	s_nop 0
	v_cndmask_b32_e32 v56, v185, v56, vcc
	v_cmp_le_i32_e32 vcc, v187, v164
	v_add_u32_e32 v187, 50, v14
	s_nop 0
	v_cndmask_b32_e32 v57, v185, v57, vcc
	v_cmp_le_i32_e32 vcc, v187, v164
	v_add_u32_e32 v187, 51, v14
	s_nop 0
	v_cndmask_b32_e32 v58, v185, v58, vcc
	v_cmp_le_i32_e32 vcc, v187, v164
	v_add_u32_e32 v187, 52, v14
	s_nop 0
	v_cndmask_b32_e32 v59, v185, v59, vcc
	v_cmp_le_i32_e32 vcc, v187, v164
	v_add_u32_e32 v187, 53, v14
	v_add_u32_e32 v14, 54, v14
	v_cndmask_b32_e32 v60, v185, v60, vcc
	v_cmp_le_i32_e32 vcc, v187, v164
	s_nop 1
	v_cndmask_b32_e32 v61, v185, v61, vcc
	v_cmp_le_i32_e32 vcc, v14, v164
	s_nop 1
	v_cndmask_b32_e32 v14, v185, v62, vcc
	v_or_b32_e32 v62, 55, v70
	v_cmp_le_i32_e32 vcc, v62, v164
	s_nop 1
	v_cndmask_b32_e32 v62, v185, v63, vcc
	v_max3_f32 v63, v15, s36, v64
	v_max3_f32 v63, v63, v65, v66
	v_max3_f32 v63, v63, v67, v68
	v_max3_f32 v63, v63, v69, v71
	v_max3_f32 v63, v63, v72, v73
	v_max3_f32 v63, v63, v74, v75
	v_max3_f32 v63, v63, v76, v77
	v_max3_f32 v63, v63, v78, v79
	v_max3_f32 v63, v63, v48, v49
	v_max3_f32 v63, v63, v50, v51
	v_max3_f32 v63, v63, v52, v53
	v_max3_f32 v63, v63, v54, v55
	v_max3_f32 v63, v63, v56, v57
	v_max3_f32 v63, v63, v58, v59
	v_max3_f32 v63, v63, v60, v61
	v_max3_f32 v63, v63, v14, v62
	v_mul_f32_e32 v63, 0x3e16c740, v63
	v_cmp_lt_i32_e32 vcc, v183, v184
	v_max_f32_e32 v0, v0, v63
	s_nop 0
	v_cndmask_b32_e32 v63, v182, v183, vcc
	v_lshlrev_b32_e32 v63, 2, v63
	ds_bpermute_b32 v70, v63, v0
	s_waitcnt lgkmcnt(0)
; #define MFMA(a, b, c) __builtin_amdgcn_mfma_f32_32x32x16_bf16((a), (b), (c), 0, 0, 0)
; DI unsigned pack2(float a, float b) { f32x2_t v = {a, b}; bf16x2_t r = __builtin_convertvector(v, bf16x2_t); return __builtin_bit_cast(unsigned, r); }
; DI float fexp2(float x) { return __builtin_amdgcn_exp2f(x); }
; DI float shx(float v, int m) { return __shfl_xor(v, m, 64); }
; template <int DQK, bool MASKED, int MODE, class MF>
; DI void attn_step(const bf16_t* sK, const bf16_t* sVt, const bf16x8 (&qf)[DQK / 16], f32x16& o0, f32x16& o1, float& m, float& l,
;                   float sc, const MF& mf, int lane, f32x16 (&s)[2], float invl, bool lanevalid = true) {
;     ...
;   float alpha = 1.f;
;   if (MODE != 2) {
;     float mx = fmaxf(m, mxr * sc);
;     mx = fmaxf(mx, shx(mx, 32));
;     if (!MASKED) mx = lanevalid ? mx : m;
;     alpha = fexp2(m - mx);
;     m = mx;
;   }
;   const float moff = (!MASKED && !lanevalid) ? 1.0e30f : m;
;   float ps = 0.f;
; #pragma unroll
;   for (int sub = 0; sub < 2; ++sub)
; #pragma unroll
;     for (int q = 0; q < 16; ++q) {
;       float pv = fexp2(__builtin_fmaf(s[sub][q], sc, -moff));
;       if (MASKED && MODE != 0) pv = (s[sub][q] > -1.0e38f) ? pv : 0.f;
;       if (MODE == 2) pv *= invl;
;       s[sub][q] = pv;
;       ps += pv;
;     }
;   if (MODE != 2) {
;     ps += shx(ps, 32);
;     l = l * alpha + ps;
;   }
;   if (MODE == 1) return;
;   if (MODE == 0) {
; #pragma unroll
;     for (int q = 0; q < 16; ++q) { o0[q] *= alpha; o1[q] *= alpha; }
;   }
; #pragma unroll
;   for (int sub = 0; sub < 2; ++sub)
; #pragma unroll
;     for (int s2 = 0; s2 < 2; ++s2) {
;       union { bf16x8 v; unsigned u[4]; } pb;
; #pragma unroll
;       for (int e = 0; e < 4; ++e) pb.u[e] = pack2(s[sub][8 * s2 + 2 * e], s[sub][8 * s2 + 2 * e + 1]);
;       o0 = MFMA(vf[sub][s2][0], pb.v, o0);
;       o1 = MFMA(vf[sub][s2][1], pb.v, o1);
;     }
; }
	s_mov_b64 s[100:101], exec
	s_mov_b64 exec, 1
	ds_write_b32 v252, v254
	s_mov_b64 exec, s[100:101]
	v_max_f32_e32 v70, v70, v70
	v_max_f32_e32 v70, v0, v70
	v_fma_f32 v0, v15, s37, -v70
	v_exp_f32_e32 v15, v0
	v_fma_f32 v0, v64, s37, -v70
	v_exp_f32_e32 v64, v0
	v_fma_f32 v0, v65, s37, -v70
	v_exp_f32_e32 v65, v0
	v_fma_f32 v66, v66, s37, -v70
	v_exp_f32_e32 v66, v66
	v_fma_f32 v67, v67, s37, -v70
	v_sub_f32_e32 v0, v186, v70
	v_add_f32_e32 v186, 0, v15
	v_exp_f32_e32 v67, v67
	v_fma_f32 v68, v68, s37, -v70
	v_add_f32_e32 v186, v64, v186
	v_exp_f32_e32 v68, v68
	v_fma_f32 v69, v69, s37, -v70
	v_add_f32_e32 v186, v65, v186
	v_exp_f32_e32 v69, v69
	v_fma_f32 v71, v71, s37, -v70
	v_add_f32_e32 v186, v66, v186
	v_exp_f32_e32 v71, v71
	v_fma_f32 v72, v72, s37, -v70
	v_add_f32_e32 v186, v67, v186
	v_exp_f32_e32 v72, v72
	v_fma_f32 v73, v73, s37, -v70
	v_add_f32_e32 v186, v68, v186
	v_exp_f32_e32 v73, v73
	v_fma_f32 v74, v74, s37, -v70
	v_add_f32_e32 v186, v69, v186
	v_exp_f32_e32 v74, v74
	v_fma_f32 v75, v75, s37, -v70
	v_add_f32_e32 v186, v71, v186
	v_exp_f32_e32 v75, v75
	v_fma_f32 v76, v76, s37, -v70
	v_add_f32_e32 v186, v72, v186
	v_exp_f32_e32 v76, v76
	v_fma_f32 v77, v77, s37, -v70
	v_add_f32_e32 v186, v73, v186
	v_exp_f32_e32 v77, v77
	v_fma_f32 v78, v78, s37, -v70
	v_add_f32_e32 v186, v74, v186
	v_exp_f32_e32 v78, v78
	v_fma_f32 v79, v79, s37, -v70
	v_add_f32_e32 v186, v75, v186
	v_exp_f32_e32 v79, v79
	v_fma_f32 v48, v48, s37, -v70
	v_add_f32_e32 v186, v76, v186
	v_exp_f32_e32 v187, v48
	v_fma_f32 v48, v49, s37, -v70
	v_add_f32_e32 v186, v77, v186
	v_exp_f32_e32 v188, v48
	v_fma_f32 v48, v50, s37, -v70
	v_add_f32_e32 v186, v78, v186
	v_exp_f32_e32 v189, v48
	v_fma_f32 v49, v51, s37, -v70
	v_add_f32_e32 v48, v79, v186
	v_exp_f32_e32 v186, v49
	v_fma_f32 v49, v52, s37, -v70
	v_add_f32_e32 v48, v187, v48
	v_exp_f32_e32 v52, v49
	v_fma_f32 v49, v53, s37, -v70
	v_add_f32_e32 v48, v188, v48
	v_exp_f32_e32 v53, v49
	v_fma_f32 v49, v54, s37, -v70
	v_add_f32_e32 v48, v189, v48
	v_exp_f32_e32 v54, v49
	v_add_f32_e32 v48, v186, v48
	v_add_f32_e32 v48, v52, v48
	v_exp_f32_e32 v0, v0
	v_add_f32_e32 v48, v53, v48
	v_add_f32_e32 v190, v54, v48
	v_fma_f32 v48, v55, s37, -v70
	v_exp_f32_e32 v55, v48
	v_fma_f32 v48, v56, s37, -v70
	v_exp_f32_e32 v56, v48
	v_pk_mul_f32 v[46:47], v[46:47], v[0:1] op_sel_hi:[1,0]
	v_pk_mul_f32 v[44:45], v[44:45], v[0:1] op_sel_hi:[1,0]
	v_pk_mul_f32 v[42:43], v[42:43], v[0:1] op_sel_hi:[1,0]
	v_pk_mul_f32 v[40:41], v[40:41], v[0:1] op_sel_hi:[1,0]
	v_pk_mul_f32 v[38:39], v[38:39], v[0:1] op_sel_hi:[1,0]
	v_pk_mul_f32 v[36:37], v[36:37], v[0:1] op_sel_hi:[1,0]
	v_pk_mul_f32 v[34:35], v[34:35], v[0:1] op_sel_hi:[1,0]
	v_pk_mul_f32 v[32:33], v[32:33], v[0:1] op_sel_hi:[1,0]
	v_pk_mul_f32 v[30:31], v[30:31], v[0:1] op_sel_hi:[1,0]
	v_cvt_pk_bf16_f32 v48, v15, v64
	v_cvt_pk_bf16_f32 v49, v65, v66
	v_cvt_pk_bf16_f32 v50, v67, v68
	v_cvt_pk_bf16_f32 v51, v69, v71
	v_pk_mul_f32 v[28:29], v[28:29], v[0:1] op_sel_hi:[1,0]
	v_pk_mul_f32 v[26:27], v[26:27], v[0:1] op_sel_hi:[1,0]
	v_pk_mul_f32 v[24:25], v[24:25], v[0:1] op_sel_hi:[1,0]
	v_pk_mul_f32 v[22:23], v[22:23], v[0:1] op_sel_hi:[1,0]
	v_pk_mul_f32 v[20:21], v[20:21], v[0:1] op_sel_hi:[1,0]
	v_pk_mul_f32 v[18:19], v[18:19], v[0:1] op_sel_hi:[1,0]
	v_pk_mul_f32 v[16:17], v[16:17], v[0:1] op_sel_hi:[1,0]
	v_mfma_f32_32x32x16_bf16 v[32:47], v[132:135], v[48:51], v[32:47]
	v_fma_f32 v57, v57, s37, -v70
	v_exp_f32_e32 v57, v57
	v_fma_f32 v58, v58, s37, -v70
	v_exp_f32_e32 v58, v58
	v_fma_f32 v59, v59, s37, -v70
	v_add_f32_e32 v15, v55, v190
	v_exp_f32_e32 v59, v59
	v_mfma_f32_32x32x16_bf16 v[16:31], v[128:131], v[48:51], v[16:31]
	v_cvt_pk_bf16_f32 v48, v72, v73
	v_cvt_pk_bf16_f32 v49, v74, v75
	v_cvt_pk_bf16_f32 v50, v76, v77
	v_cvt_pk_bf16_f32 v51, v78, v79
	v_add_f32_e32 v15, v56, v15
	v_add_f32_e32 v15, v57, v15
	v_fma_f32 v14, v14, s37, -v70
	v_mfma_f32_32x32x16_bf16 v[32:47], v[124:127], v[48:51], v[32:47]
	v_add_f32_e32 v15, v58, v15
	v_exp_f32_e32 v14, v14
	v_add_f32_e32 v15, v59, v15
	v_mfma_f32_32x32x16_bf16 v[16:31], v[120:123], v[48:51], v[16:31]
	v_fma_f32 v48, v60, s37, -v70
	v_exp_f32_e32 v60, v48
	v_cvt_pk_bf16_f32 v48, v187, v188
	v_cvt_pk_bf16_f32 v49, v189, v186
	v_cvt_pk_bf16_f32 v50, v52, v53
	v_cvt_pk_bf16_f32 v51, v54, v55
	v_fma_f32 v52, v61, s37, -v70
	v_exp_f32_e32 v52, v52
	v_mfma_f32_32x32x16_bf16 v[32:47], v[116:119], v[48:51], v[32:47]
	v_fma_f32 v53, v62, s37, -v70
	v_exp_f32_e32 v53, v53
	v_add_f32_e32 v15, v60, v15
	v_mov_b32_e32 v186, v70
	v_mfma_f32_32x32x16_bf16 v[16:31], v[10:13], v[48:51], v[16:31]
	v_add_f32_e32 v10, v52, v15
	v_add_f32_e32 v10, v14, v10
	v_add_f32_e32 v15, v53, v10
	v_cvt_pk_bf16_f32 v10, v56, v57
	v_cvt_pk_bf16_f32 v11, v58, v59
	v_cvt_pk_bf16_f32 v12, v60, v52
	v_cvt_pk_bf16_f32 v13, v14, v53
	s_nop 1
	v_mfma_f32_32x32x16_bf16 v[32:47], v[6:9], v[10:13], v[32:47]
	ds_bpermute_b32 v6, v63, v15
	s_waitcnt lgkmcnt(0)
	v_add_f32_e32 v6, v15, v6
	v_fmac_f32_e32 v6, v165, v0
	v_mfma_f32_32x32x16_bf16 v[16:31], v[2:5], v[10:13], v[16:31]
	v_mov_b32_e32 v165, v6

; DI void phase_attn_mla(const Params& P, bf16_t* og, unsigned char* smem, int L, int G) {
;     ...
;       if (key0 <= t0 + 31) {
.Lmy_mla_skip:
	s_mov_b64 exec, 1
	ds_write_b32 v252, v254
	s_branch .LBB0_791
